# attention loop: mid-tile barrier dropped (one s_barrier per tile per half) + V fragment reads issued right after the MFMA that frees their registers; placement pads kept
# speedup vs baseline: 1.0132x; 1.0132x over previous
.LqL_ldsb:
	s_add_i32 s33, s65, 0x10000
	s_and_b32 s33, s33, 0x18000
	s_add_i32 s33, s57, s33
	v_lshlrev_b32_e32 v198, 1, v150
	v_mfma_f32_32x32x16_bf16 v[32:47], v[242:245], v[64:67], v[32:47]
	s_mov_b32 m0, s33
	v_exp_f32_e32 v72, v72
	v_exp_f32_e32 v73, v73
	v_exp_f32_e32 v74, v74
	v_exp_f32_e32 v75, v75
	v_add_f32_e32 v184, v72, v73
	s_and_b32 s100, s65, 0x18000
	v_add_u32_e32 v194, s100, v149
	v_add_u32_e32 v195, v194, v157
	v_add_u32_e32 v196, v194, v193
	ds_read_b128 v[242:245], v218 offset:16384
	global_load_lds_dwordx4 v188, s[70:71]
	v_mfma_f32_32x32x16_bf16 v[48:63], v[246:249], v[64:67], v[48:63]
	v_exp_f32_e32 v76, v76
	v_exp_f32_e32 v77, v77
	v_cvt_pk_bf16_f32 v68, v72, v73
	v_add_f32_e32 v185, v74, v75
	v_cvt_pk_bf16_f32 v69, v74, v75
	v_add_u32_e32 v197, v194, v208
	v_add_u32_e32 v194, v194, v209
	ds_read_b128 v[132:135], v195
	ds_read_b128 v[116:119], v195 offset:4096
	ds_read_b128 v[246:249], v218 offset:20480
	v_mfma_f32_32x32x16_bf16 v[16:31], v[250:253], v[64:67], v[16:31]
	s_add_u32 s100, s70, 0x40000
	s_addc_u32 s101, s71, 0
	s_add_i32 m0, s33, 0x2000
	v_exp_f32_e32 v78, v78
	v_exp_f32_e32 v79, v79
	v_add_f32_e32 v186, v76, v77
	v_cvt_pk_bf16_f32 v70, v76, v77
	v_add_f32_e32 v184, v184, v185
	ds_read_b128 v[136:139], v196
	ds_read_b128 v[120:123], v196 offset:4096
	ds_read_b128 v[140:143], v197
	ds_read_b128 v[124:127], v197 offset:4096
	ds_read_b128 v[250:253], v218 offset:24576
	global_load_lds_dwordx4 v188, s[100:101]
	v_mfma_f32_32x32x16_bf16 v[0:15], v[200:203], v[64:67], v[0:15]
	v_add_f32_e32 v187, v78, v79
	v_cvt_pk_bf16_f32 v71, v78, v79
	v_add_f32_e32 v186, v186, v187
	v_add_f32_e32 v184, v184, v186
	v_add_f32_e32 v206, v206, v184
	ds_read_b128 v[128:131], v194
	ds_read_b128 v[112:115], v194 offset:4096
	ds_read_b128 v[200:203], v218 offset:28672
	v_mfma_f32_32x32x16_bf16 v[32:47], v[220:223], v[68:71], v[32:47]
	s_add_i32 m0, s33, 0x4000
	v_exp_f32_e32 v80, v80
	v_exp_f32_e32 v81, v81
	v_exp_f32_e32 v82, v82
	v_exp_f32_e32 v83, v83
	v_add_f32_e32 v184, v80, v81
	ds_read_b128 v[220:223], v219 offset:16384
	global_load_lds_dwordx4 v198, s[66:67]
	v_mfma_f32_32x32x16_bf16 v[48:63], v[224:227], v[68:71], v[48:63]
	v_exp_f32_e32 v84, v84
	v_exp_f32_e32 v85, v85
	v_cvt_pk_bf16_f32 v72, v80, v81
	v_add_f32_e32 v185, v82, v83
	v_cvt_pk_bf16_f32 v73, v82, v83
	ds_read_b128 v[224:227], v219 offset:20480
	v_mfma_f32_32x32x16_bf16 v[16:31], v[234:237], v[68:71], v[16:31]
	s_add_u32 s100, s66, 0x40000
	s_addc_u32 s101, s67, 0
	s_add_i32 m0, s33, 0x6000
	v_exp_f32_e32 v86, v86
	v_exp_f32_e32 v87, v87
	v_add_f32_e32 v186, v84, v85
	v_cvt_pk_bf16_f32 v74, v84, v85
	v_add_f32_e32 v184, v184, v185
	ds_read_b128 v[234:237], v219 offset:24576
	global_load_lds_dwordx4 v198, s[100:101]
	v_mfma_f32_32x32x16_bf16 v[0:15], v[238:241], v[68:71], v[0:15]
	v_add_f32_e32 v187, v86, v87
	v_cvt_pk_bf16_f32 v75, v86, v87
	v_add_f32_e32 v186, v186, v187
	v_add_f32_e32 v184, v184, v186
	v_add_f32_e32 v206, v206, v184
	ds_read_b128 v[238:241], v219 offset:28672
	s_waitcnt lgkmcnt(4)
	v_mfma_f32_32x32x16_bf16 v[32:47], v[242:245], v[72:75], v[32:47]
	s_add_u32 s100, s70, 0x1000
	s_addc_u32 s101, s71, 0
	s_add_i32 m0, s33, 0x1000
	v_exp_f32_e32 v88, v88
	v_exp_f32_e32 v89, v89
	v_exp_f32_e32 v90, v90
	v_exp_f32_e32 v91, v91
	v_add_f32_e32 v184, v88, v89
	global_load_lds_dwordx4 v188, s[100:101]
	v_mfma_f32_32x32x16_bf16 v[48:63], v[246:249], v[72:75], v[48:63]
	v_exp_f32_e32 v92, v92
	v_exp_f32_e32 v93, v93
	v_cvt_pk_bf16_f32 v76, v88, v89
	v_add_f32_e32 v185, v90, v91
	v_cvt_pk_bf16_f32 v77, v90, v91
	v_mfma_f32_32x32x16_bf16 v[16:31], v[250:253], v[72:75], v[16:31]
	s_add_u32 s100, s70, 0x41000
	s_addc_u32 s101, s71, 0
	s_add_i32 m0, s33, 0x3000
	v_exp_f32_e32 v94, v94
	v_exp_f32_e32 v95, v95
	v_add_f32_e32 v186, v92, v93
	v_cvt_pk_bf16_f32 v78, v92, v93
	v_add_f32_e32 v184, v184, v185
	global_load_lds_dwordx4 v188, s[100:101]
	v_mfma_f32_32x32x16_bf16 v[0:15], v[200:203], v[72:75], v[0:15]
	v_add_f32_e32 v187, v94, v95
	v_cvt_pk_bf16_f32 v79, v94, v95
	v_add_f32_e32 v186, v186, v187
	v_add_f32_e32 v184, v184, v186
	v_add_f32_e32 v206, v206, v184
	s_waitcnt lgkmcnt(0)
	v_mfma_f32_32x32x16_bf16 v[32:47], v[220:223], v[76:79], v[32:47]
	s_add_u32 s100, s66, 0x20000
	s_addc_u32 s101, s67, 0
	s_add_i32 m0, s33, 0x5000
	s_nop 0
	global_load_lds_dwordx4 v198, s[100:101]
	v_mfma_f32_32x32x16_bf16 v[48:63], v[224:227], v[76:79], v[48:63]
	s_add_u32 s100, s66, 0x60000
	s_addc_u32 s101, s67, 0
	s_add_i32 m0, s33, 0x7000
	s_nop 0
	global_load_lds_dwordx4 v198, s[100:101]
	s_waitcnt lgkmcnt(0)
	s_add_i32 s65, s65, 0x8000
	s_addk_i32 s23, 0x100
	s_add_i32 s36, s36, 64
	s_mov_b32 s33, s54
	s_setprio 0
	s_cmpk_eq_i32 s23, 0x1e00
	v_mfma_f32_32x32x16_bf16 v[16:31], v[234:237], v[76:79], v[16:31]
	v_mfma_f32_32x32x16_bf16 v[0:15], v[238:241], v[76:79], v[0:15]
	s_cbranch_scc0 .LqL_top
	s_branch .LBB0_284

.LqT_g0:
	v_exp_f32_e32 v64, v64
	v_exp_f32_e32 v65, v65
	v_exp_f32_e32 v66, v66
	v_exp_f32_e32 v67, v67
	v_add_f32_e32 v184, v64, v65
	v_exp_f32_e32 v68, v68
	v_exp_f32_e32 v69, v69
	v_cvt_pk_bf16_f32 v64, v64, v65
	v_add_f32_e32 v185, v66, v67
	v_cvt_pk_bf16_f32 v65, v66, v67
	v_exp_f32_e32 v70, v70
	v_exp_f32_e32 v71, v71
	v_add_f32_e32 v186, v68, v69
	v_cvt_pk_bf16_f32 v66, v68, v69
	v_add_f32_e32 v184, v184, v185
	v_add_f32_e32 v187, v70, v71
	v_cvt_pk_bf16_f32 v67, v70, v71
	v_add_f32_e32 v186, v186, v187
	v_add_f32_e32 v184, v184, v186
	v_add_f32_e32 v206, v206, v184
	s_waitcnt vmcnt(0) lgkmcnt(0)
	s_add_i32 s54, s33, 1
	s_setprio 1
	v_mfma_f32_32x32x16_bf16 v[32:47], v[242:245], v[64:67], v[32:47]
	v_exp_f32_e32 v72, v72
	v_exp_f32_e32 v73, v73
	v_exp_f32_e32 v74, v74
	v_exp_f32_e32 v75, v75
	v_add_f32_e32 v184, v72, v73
	s_and_b32 s100, s65, 0x18000
	v_add_u32_e32 v194, s100, v149
	v_add_u32_e32 v195, v194, v157
	v_add_u32_e32 v196, v194, v193
	ds_read_b128 v[242:245], v218 offset:16384
	v_mfma_f32_32x32x16_bf16 v[48:63], v[246:249], v[64:67], v[48:63]
	v_exp_f32_e32 v76, v76
	v_exp_f32_e32 v77, v77
	v_cvt_pk_bf16_f32 v68, v72, v73
	v_add_f32_e32 v185, v74, v75
	v_cvt_pk_bf16_f32 v69, v74, v75
	v_add_u32_e32 v197, v194, v208
	v_add_u32_e32 v194, v194, v209
	ds_read_b128 v[132:135], v195
	ds_read_b128 v[116:119], v195 offset:4096
	ds_read_b128 v[246:249], v218 offset:20480
	v_mfma_f32_32x32x16_bf16 v[16:31], v[250:253], v[64:67], v[16:31]
	v_exp_f32_e32 v78, v78
	v_exp_f32_e32 v79, v79
	v_add_f32_e32 v186, v76, v77
	v_cvt_pk_bf16_f32 v70, v76, v77
	v_add_f32_e32 v184, v184, v185
	ds_read_b128 v[136:139], v196
	ds_read_b128 v[120:123], v196 offset:4096
	ds_read_b128 v[140:143], v197
	ds_read_b128 v[124:127], v197 offset:4096
	ds_read_b128 v[250:253], v218 offset:24576
	v_mfma_f32_32x32x16_bf16 v[0:15], v[200:203], v[64:67], v[0:15]
	v_add_f32_e32 v187, v78, v79
	v_cvt_pk_bf16_f32 v71, v78, v79
	v_add_f32_e32 v186, v186, v187
	v_add_f32_e32 v184, v184, v186
	v_add_f32_e32 v206, v206, v184
	ds_read_b128 v[128:131], v194
	ds_read_b128 v[112:115], v194 offset:4096
	ds_read_b128 v[200:203], v218 offset:28672
	v_mfma_f32_32x32x16_bf16 v[32:47], v[220:223], v[68:71], v[32:47]
	v_exp_f32_e32 v80, v80
	v_exp_f32_e32 v81, v81
	v_exp_f32_e32 v82, v82
	v_exp_f32_e32 v83, v83
	v_add_f32_e32 v184, v80, v81
	ds_read_b128 v[220:223], v219 offset:16384
	v_mfma_f32_32x32x16_bf16 v[48:63], v[224:227], v[68:71], v[48:63]
	v_exp_f32_e32 v84, v84
	v_exp_f32_e32 v85, v85
	v_cvt_pk_bf16_f32 v72, v80, v81
	v_add_f32_e32 v185, v82, v83
	v_cvt_pk_bf16_f32 v73, v82, v83
	ds_read_b128 v[224:227], v219 offset:20480
	v_mfma_f32_32x32x16_bf16 v[16:31], v[234:237], v[68:71], v[16:31]
	v_exp_f32_e32 v86, v86
	v_exp_f32_e32 v87, v87
	v_add_f32_e32 v186, v84, v85
	v_cvt_pk_bf16_f32 v74, v84, v85
	v_add_f32_e32 v184, v184, v185
	ds_read_b128 v[234:237], v219 offset:24576
	v_mfma_f32_32x32x16_bf16 v[0:15], v[238:241], v[68:71], v[0:15]
	v_add_f32_e32 v187, v86, v87
	v_cvt_pk_bf16_f32 v75, v86, v87
	v_add_f32_e32 v186, v186, v187
	v_add_f32_e32 v184, v184, v186
	v_add_f32_e32 v206, v206, v184
	ds_read_b128 v[238:241], v219 offset:28672
	s_waitcnt lgkmcnt(4)
	v_mfma_f32_32x32x16_bf16 v[32:47], v[242:245], v[72:75], v[32:47]
	v_exp_f32_e32 v88, v88
	v_exp_f32_e32 v89, v89
	v_exp_f32_e32 v90, v90
	v_exp_f32_e32 v91, v91
	v_add_f32_e32 v184, v88, v89
	v_mfma_f32_32x32x16_bf16 v[48:63], v[246:249], v[72:75], v[48:63]
	v_exp_f32_e32 v92, v92
	v_exp_f32_e32 v93, v93
	v_cvt_pk_bf16_f32 v76, v88, v89
	v_add_f32_e32 v185, v90, v91
	v_cvt_pk_bf16_f32 v77, v90, v91
	v_mfma_f32_32x32x16_bf16 v[16:31], v[250:253], v[72:75], v[16:31]
	v_exp_f32_e32 v94, v94
	v_exp_f32_e32 v95, v95
	v_add_f32_e32 v186, v92, v93
	v_cvt_pk_bf16_f32 v78, v92, v93
	v_add_f32_e32 v184, v184, v185
	v_mfma_f32_32x32x16_bf16 v[0:15], v[200:203], v[72:75], v[0:15]
	v_add_f32_e32 v187, v94, v95
	v_cvt_pk_bf16_f32 v79, v94, v95
	v_add_f32_e32 v186, v186, v187
	v_add_f32_e32 v184, v184, v186
	v_add_f32_e32 v206, v206, v184
	s_waitcnt lgkmcnt(0)
	v_mfma_f32_32x32x16_bf16 v[32:47], v[220:223], v[76:79], v[32:47]
	v_mfma_f32_32x32x16_bf16 v[48:63], v[224:227], v[76:79], v[48:63]
	s_waitcnt lgkmcnt(0)
	s_barrier
	s_add_i32 s65, s65, 0x8000
	s_addk_i32 s23, 0x100
	s_add_i32 s36, s36, 64
	s_mov_b32 s33, s54
	s_setprio 0
	s_cmpk_eq_i32 s23, 0x1e00
	v_mfma_f32_32x32x16_bf16 v[16:31], v[234:237], v[76:79], v[16:31]
	v_mfma_f32_32x32x16_bf16 v[0:15], v[238:241], v[76:79], v[0:15]
	s_cbranch_scc0 .LqT_top
	s_branch .LBB0_284

.LqT_rescale:
	s_mov_b32 s98, 0
	ds_bpermute_b32 v129, v210, v128
	s_waitcnt lgkmcnt(0)
	v_max_f32_e32 v129, v129, v129
	v_max_f32_e32 v128, v128, v129
	v_cmp_lt_f32_e32 vcc, s88, v128
	s_nop 0
	s_nop 0
	v_cndmask_b32_e32 v128, 0, v128, vcc
	v_exp_f32_e64 v130, -v128
	v_pk_add_f32 v[64:65], v[64:65], v[128:129] op_sel_hi:[1,0] neg_lo:[0,1] neg_hi:[0,1]
	v_pk_add_f32 v[80:81], v[80:81], v[128:129] op_sel_hi:[1,0] neg_lo:[0,1] neg_hi:[0,1]
	v_pk_add_f32 v[66:67], v[66:67], v[128:129] op_sel_hi:[1,0] neg_lo:[0,1] neg_hi:[0,1]
	v_pk_mul_f32 v[46:47], v[46:47], v[130:131] op_sel_hi:[1,0]
	v_pk_mul_f32 v[44:45], v[44:45], v[130:131] op_sel_hi:[1,0]
	v_pk_mul_f32 v[42:43], v[42:43], v[130:131] op_sel_hi:[1,0]
	v_pk_mul_f32 v[40:41], v[40:41], v[130:131] op_sel_hi:[1,0]
	v_pk_mul_f32 v[38:39], v[38:39], v[130:131] op_sel_hi:[1,0]
	v_pk_mul_f32 v[36:37], v[36:37], v[130:131] op_sel_hi:[1,0]
	v_pk_mul_f32 v[34:35], v[34:35], v[130:131] op_sel_hi:[1,0]
	v_pk_mul_f32 v[32:33], v[32:33], v[130:131] op_sel_hi:[1,0]
	v_pk_mul_f32 v[62:63], v[62:63], v[130:131] op_sel_hi:[1,0]
	v_pk_mul_f32 v[60:61], v[60:61], v[130:131] op_sel_hi:[1,0]
	v_pk_mul_f32 v[58:59], v[58:59], v[130:131] op_sel_hi:[1,0]
	v_pk_mul_f32 v[56:57], v[56:57], v[130:131] op_sel_hi:[1,0]
	v_pk_mul_f32 v[54:55], v[54:55], v[130:131] op_sel_hi:[1,0]
	v_pk_mul_f32 v[52:53], v[52:53], v[130:131] op_sel_hi:[1,0]
	v_pk_mul_f32 v[50:51], v[50:51], v[130:131] op_sel_hi:[1,0]
	v_pk_mul_f32 v[48:49], v[48:49], v[130:131] op_sel_hi:[1,0]
	v_pk_mul_f32 v[30:31], v[30:31], v[130:131] op_sel_hi:[1,0]
	v_pk_mul_f32 v[28:29], v[28:29], v[130:131] op_sel_hi:[1,0]
	v_pk_mul_f32 v[26:27], v[26:27], v[130:131] op_sel_hi:[1,0]
	v_pk_mul_f32 v[24:25], v[24:25], v[130:131] op_sel_hi:[1,0]
	v_pk_mul_f32 v[22:23], v[22:23], v[130:131] op_sel_hi:[1,0]
	v_pk_mul_f32 v[20:21], v[20:21], v[130:131] op_sel_hi:[1,0]
	v_pk_mul_f32 v[18:19], v[18:19], v[130:131] op_sel_hi:[1,0]
	v_pk_mul_f32 v[16:17], v[16:17], v[130:131] op_sel_hi:[1,0]
	v_pk_mul_f32 v[14:15], v[14:15], v[130:131] op_sel_hi:[1,0]
	v_pk_mul_f32 v[12:13], v[12:13], v[130:131] op_sel_hi:[1,0]
	v_pk_mul_f32 v[10:11], v[10:11], v[130:131] op_sel_hi:[1,0]
	v_pk_mul_f32 v[8:9], v[8:9], v[130:131] op_sel_hi:[1,0]
	v_pk_mul_f32 v[6:7], v[6:7], v[130:131] op_sel_hi:[1,0]
	v_pk_mul_f32 v[4:5], v[4:5], v[130:131] op_sel_hi:[1,0]
	v_pk_mul_f32 v[2:3], v[2:3], v[130:131] op_sel_hi:[1,0]
	v_pk_mul_f32 v[0:1], v[0:1], v[130:131] op_sel_hi:[1,0]
	v_mov_b32_e32 v131, v128
	v_pk_add_f32 v[82:83], v[82:83], v[128:129] op_sel_hi:[1,0] neg_lo:[0,1] neg_hi:[0,1]
	v_pk_add_f32 v[68:69], v[68:69], v[128:129] op_sel_hi:[1,0] neg_lo:[0,1] neg_hi:[0,1]
	v_pk_add_f32 v[84:85], v[84:85], v[128:129] op_sel_hi:[1,0] neg_lo:[0,1] neg_hi:[0,1]
	v_pk_add_f32 v[70:71], v[70:71], v[128:129] op_sel_hi:[1,0] neg_lo:[0,1] neg_hi:[0,1]
	v_pk_add_f32 v[86:87], v[86:87], v[128:129] op_sel_hi:[1,0] neg_lo:[0,1] neg_hi:[0,1]
	v_pk_add_f32 v[72:73], v[72:73], v[128:129] op_sel_hi:[1,0] neg_lo:[0,1] neg_hi:[0,1]
	v_pk_add_f32 v[88:89], v[88:89], v[128:129] op_sel_hi:[1,0] neg_lo:[0,1] neg_hi:[0,1]
	v_pk_add_f32 v[74:75], v[74:75], v[128:129] op_sel_hi:[1,0] neg_lo:[0,1] neg_hi:[0,1]
	v_pk_add_f32 v[90:91], v[90:91], v[128:129] op_sel_hi:[1,0] neg_lo:[0,1] neg_hi:[0,1]
	v_pk_add_f32 v[76:77], v[76:77], v[128:129] op_sel_hi:[1,0] neg_lo:[0,1] neg_hi:[0,1]
	v_pk_add_f32 v[92:93], v[92:93], v[128:129] op_sel_hi:[1,0] neg_lo:[0,1] neg_hi:[0,1]
	v_pk_add_f32 v[78:79], v[78:79], v[128:129] op_sel_hi:[1,0] neg_lo:[0,1] neg_hi:[0,1]
	v_pk_add_f32 v[94:95], v[94:95], v[128:129] op_sel_hi:[1,0] neg_lo:[0,1] neg_hi:[0,1]
	v_pk_add_f32 v[128:129], v[206:207], v[130:131]
	v_pk_mul_f32 v[206:207], v[206:207], v[130:131]
	s_nop 0
	v_mov_b32_e32 v207, v129
	s_branch .LqT_g0
	s_nop 0
	s_nop 0
